# barrier 9 (R2_0 to QKV1) made row-block-group-local plus a global D0-done counter; barrier 7 stays global
# speedup vs baseline: 1.0282x; 1.0042x over previous
.LBB0_124:
	s_or_b64 exec, exec, s[4:5]
	s_waitcnt vmcnt(0)
	s_barrier
	s_mov_b64 s[4:5], exec
	v_readlane_b32 s0, v219, 25
	v_readlane_b32 s1, v219, 26
	s_and_b64 s[0:1], s[4:5], s[0:1]
	s_mov_b64 exec, s[0:1]
	s_cbranch_execz .LBB0_176
	v_readlane_b32 s0, v219, 27
	v_readlane_b32 s1, v219, 28
	v_readlane_b32 s2, v219, 30
	s_waitcnt vmcnt(0) lgkmcnt(0)
	buffer_inv sc1
	s_and_b32 s3, s2, 31
	s_lshl_b32 s3, s3, 7
	s_add_i32 s3, s3, 64
	v_mov_b32_e32 v1, s3
	v_mov_b32_e32 v0, 1
	s_nop 1
	global_atomic_add v1, v0, s[0:1]
	s_mov_b32 s15, 0
.Lgb2_spin:
	global_load_dword v2, v1, s[0:1] sc1
	s_waitcnt vmcnt(0)
	v_readfirstlane_b32 s13, v2
	s_nop 1
	s_cmp_lt_u32 s13, 8
	s_cbranch_scc1 .Lgb2_again
	s_branch .Lgb2_done
.Lgb2_again:
	s_sleep 1
	s_add_i32 s15, s15, 1
	s_cmp_lt_u32 s15, 0x200000
	s_cbranch_scc1 .Lgb2_spin

.LBB0_512:
	s_waitcnt vmcnt(0)
	s_waitcnt vmcnt(0) lgkmcnt(0)
	s_barrier
	s_mov_b64 s[4:5], exec
	v_readlane_b32 s0, v219, 25
	v_readlane_b32 s1, v219, 26
	s_and_b64 s[0:1], s[4:5], s[0:1]
	s_mov_b64 exec, s[0:1]
	s_cbranch_execz .LBB0_564
	v_readlane_b32 s0, v219, 27
	v_readlane_b32 s1, v219, 28
	v_readlane_b32 s2, v219, 30
	s_waitcnt vmcnt(0) lgkmcnt(0)
	buffer_inv sc1
	s_and_b32 s3, s2, 31
	s_lshl_b32 s3, s3, 7
	s_add_i32 s3, s3, 64
	v_mov_b32_e32 v1, s3
	v_mov_b32_e32 v0, 1
	s_nop 1
	global_atomic_add v1, v0, s[0:1]
	s_mov_b32 s15, 0
.Lgb5_spin:
	global_load_dword v2, v1, s[0:1] sc1
	s_waitcnt vmcnt(0)
	v_readfirstlane_b32 s13, v2
	s_nop 1
	s_cmp_lt_u32 s13, 16
	s_cbranch_scc1 .Lgb5_again
	s_branch .Lgb5_done

.Lgb6_spin:
	global_load_dword v2, v1, s[0:1] sc1
	s_waitcnt vmcnt(0)
	v_readfirstlane_b32 s13, v2
	s_nop 1
	s_cmp_lt_u32 s13, 24
	s_cbranch_scc1 .Lgb6_again
	s_branch .Lgb6_done

.LBB0_809:
	s_waitcnt vmcnt(0)
	s_waitcnt vmcnt(0) lgkmcnt(0)
	s_barrier
	s_mov_b64 s[6:7], exec
	v_readlane_b32 s0, v219, 25
	v_readlane_b32 s1, v219, 26
	s_and_b64 s[0:1], s[6:7], s[0:1]
	s_mov_b64 exec, s[0:1]
	s_cbranch_execz .LBB0_861
	v_readlane_b32 s0, v219, 27
	v_readlane_b32 s1, v219, 28
	v_readlane_b32 s2, v219, 30
	s_waitcnt vmcnt(0) lgkmcnt(0)
	buffer_inv sc1
	s_and_b32 s3, s2, 31
	s_lshl_b32 s3, s3, 7
	s_add_i32 s3, s3, 64
	v_mov_b32_e32 v1, s3
	v_mov_b32_e32 v0, 1
	s_nop 1
	global_atomic_add v1, v0, s[0:1]
	v_mov_b32_e32 v2, 0x1040
	global_atomic_add v2, v0, s[0:1]
	s_mov_b32 s15, 0
.Lgb8_spin:
	global_load_dword v2, v1, s[0:1] sc1
	s_waitcnt vmcnt(0)
	v_readfirstlane_b32 s13, v2
	s_nop 1
	s_cmp_lt_u32 s13, 32
	s_cbranch_scc1 .Lgb8_again
	s_branch .Lgb8_done

.LBB0_866:
	s_or_b64 exec, exec, s[6:7]
	s_waitcnt vmcnt(0)
	s_barrier
	s_mov_b64 s[6:7], exec
	v_readlane_b32 s0, v219, 25
	v_readlane_b32 s1, v219, 26
	s_and_b64 s[0:1], s[6:7], s[0:1]
	s_mov_b64 exec, s[0:1]
	s_cbranch_execz .LBB0_918
	v_readlane_b32 s0, v219, 27
	v_readlane_b32 s1, v219, 28
	v_readlane_b32 s2, v219, 30
	s_waitcnt vmcnt(0) lgkmcnt(0)
	buffer_inv sc1
	s_and_b32 s3, s2, 31
	s_lshl_b32 s3, s3, 7
	s_add_i32 s3, s3, 64
	v_mov_b32_e32 v1, s3
	v_mov_b32_e32 v0, 1
	s_nop 1
	global_atomic_add v1, v0, s[0:1]
	s_mov_b32 s15, 0
	v_mov_b32_e32 v0, 0x1040
.Lgb9_spin:
	global_load_dword v2, v1, s[0:1] sc1
	global_load_dword v0, v0, s[0:1] sc1
	s_waitcnt vmcnt(0)
	v_readfirstlane_b32 s13, v2
	v_readfirstlane_b32 s14, v0
	v_mov_b32_e32 v0, 0x1040
	s_nop 1
	s_cmp_lt_u32 s13, 40
	s_cbranch_scc1 .Lgb9_again
	s_cmp_lt_u32 s14, 256
	s_cbranch_scc1 .Lgb9_again
	s_branch .Lgb9_done

.LBB0_1035:
	s_waitcnt vmcnt(0)
	s_waitcnt vmcnt(0) lgkmcnt(0)
	s_barrier
	s_mov_b64 s[6:7], exec
	v_readlane_b32 s0, v219, 25
	v_readlane_b32 s1, v219, 26
	s_and_b64 s[0:1], s[6:7], s[0:1]
	s_mov_b64 exec, s[0:1]
	s_cbranch_execz .LBB0_1087
	v_readlane_b32 s0, v219, 27
	v_readlane_b32 s1, v219, 28
	v_readlane_b32 s2, v219, 29
	v_mov_b32_e32 v0, 0x24000
	s_waitcnt vmcnt(0) lgkmcnt(0)
	buffer_inv sc1
	ds_read_b32 v2, v0
	ds_read_b32 v0, v0 offset:4
	s_lshl_b32 s3, s2, 8
	s_add_i32 s14, s3, 0x2400
	s_add_i32 s3, s3, 0x1400
	v_mov_b32_e32 v1, s3
	s_waitcnt lgkmcnt(0)
	v_readfirstlane_b32 s10, v2
	v_readfirstlane_b32 s11, v0
	v_mov_b32_e32 v0, 1
	s_nop 1
	global_atomic_add v2, v1, v0, s[0:1] sc0
	s_mul_i32 s10, s10, 5
	s_mul_i32 s11, s11, 5
	s_waitcnt vmcnt(0)
	v_readfirstlane_b32 s13, v2
	s_nop 1
	s_add_i32 s13, s13, 1
	s_cmp_lg_u32 s13, s10
	s_cbranch_scc1 .Lnb10_wait
	v_mov_b32_e32 v1, 0x3400
	global_atomic_add v2, v1, v0, s[0:1] sc0
	s_waitcnt vmcnt(0)
	v_readfirstlane_b32 s13, v2
	s_nop 1
	s_add_i32 s13, s13, 1
	s_cmp_lg_u32 s13, s11
	s_cbranch_scc1 .Lnb10_wait
	v_mov_b32_e32 v1, 0x2400
	global_atomic_add v1, v0, s[0:1]
	global_atomic_add v1, v0, s[0:1] offset:256
	global_atomic_add v1, v0, s[0:1] offset:512
	global_atomic_add v1, v0, s[0:1] offset:768
	global_atomic_add v1, v0, s[0:1] offset:1024
	global_atomic_add v1, v0, s[0:1] offset:1280
	global_atomic_add v1, v0, s[0:1] offset:1536
	global_atomic_add v1, v0, s[0:1] offset:1792
	global_atomic_add v1, v0, s[0:1] offset:2048
	global_atomic_add v1, v0, s[0:1] offset:2304
	global_atomic_add v1, v0, s[0:1] offset:2560
	global_atomic_add v1, v0, s[0:1] offset:2816
	global_atomic_add v1, v0, s[0:1] offset:3072
	global_atomic_add v1, v0, s[0:1] offset:3328
	global_atomic_add v1, v0, s[0:1] offset:3584
	global_atomic_add v1, v0, s[0:1] offset:3840

.LBB0_1120:
	s_waitcnt vmcnt(0)
	s_barrier
	s_mov_b64 s[6:7], exec
	v_readlane_b32 s0, v219, 25
	v_readlane_b32 s1, v219, 26
	s_and_b64 s[0:1], s[6:7], s[0:1]
	s_mov_b64 exec, s[0:1]
	s_cbranch_execz .LBB0_1172
	v_readlane_b32 s0, v219, 27
	v_readlane_b32 s1, v219, 28
	v_readlane_b32 s2, v219, 29
	v_mov_b32_e32 v0, 0x24000
	s_waitcnt vmcnt(0) lgkmcnt(0)
	buffer_inv sc1
	ds_read_b32 v2, v0
	ds_read_b32 v0, v0 offset:4
	s_lshl_b32 s3, s2, 8
	s_add_i32 s14, s3, 0x2400
	s_add_i32 s3, s3, 0x1400
	v_mov_b32_e32 v1, s3
	s_waitcnt lgkmcnt(0)
	v_readfirstlane_b32 s10, v2
	v_readfirstlane_b32 s11, v0
	v_mov_b32_e32 v0, 1
	s_nop 1
	global_atomic_add v2, v1, v0, s[0:1] sc0
	s_mul_i32 s10, s10, 6
	s_mul_i32 s11, s11, 6
	s_waitcnt vmcnt(0)
	v_readfirstlane_b32 s13, v2
	s_nop 1
	s_add_i32 s13, s13, 1
	s_cmp_lg_u32 s13, s10
	s_cbranch_scc1 .Lnb11_wait
	v_mov_b32_e32 v1, 0x3400
	global_atomic_add v2, v1, v0, s[0:1] sc0
	s_waitcnt vmcnt(0)
	v_readfirstlane_b32 s13, v2
	s_nop 1
	s_add_i32 s13, s13, 1
	s_cmp_lg_u32 s13, s11
	s_cbranch_scc1 .Lnb11_wait
	v_mov_b32_e32 v1, 0x2400
	global_atomic_add v1, v0, s[0:1]
	global_atomic_add v1, v0, s[0:1] offset:256
	global_atomic_add v1, v0, s[0:1] offset:512
	global_atomic_add v1, v0, s[0:1] offset:768
	global_atomic_add v1, v0, s[0:1] offset:1024
	global_atomic_add v1, v0, s[0:1] offset:1280
	global_atomic_add v1, v0, s[0:1] offset:1536
	global_atomic_add v1, v0, s[0:1] offset:1792
	global_atomic_add v1, v0, s[0:1] offset:2048
	global_atomic_add v1, v0, s[0:1] offset:2304
	global_atomic_add v1, v0, s[0:1] offset:2560
	global_atomic_add v1, v0, s[0:1] offset:2816
	global_atomic_add v1, v0, s[0:1] offset:3072
	global_atomic_add v1, v0, s[0:1] offset:3328
	global_atomic_add v1, v0, s[0:1] offset:3584
	global_atomic_add v1, v0, s[0:1] offset:3840

.LBB0_1236:
	s_waitcnt vmcnt(0)
	s_waitcnt vmcnt(0) lgkmcnt(0)
	s_barrier
	s_mov_b64 s[6:7], exec
	v_readlane_b32 s0, v219, 25
	v_readlane_b32 s1, v219, 26
	s_and_b64 s[0:1], s[6:7], s[0:1]
	s_mov_b64 exec, s[0:1]
	s_cbranch_execz .LBB0_1288
	v_readlane_b32 s0, v219, 27
	v_readlane_b32 s1, v219, 28
	v_readlane_b32 s2, v219, 30
	s_waitcnt vmcnt(0) lgkmcnt(0)
	buffer_inv sc1
	s_and_b32 s3, s2, 31
	s_lshl_b32 s3, s3, 7
	s_add_i32 s3, s3, 64
	v_mov_b32_e32 v1, s3
	v_mov_b32_e32 v0, 1
	s_nop 1
	global_atomic_add v1, v0, s[0:1]
	s_mov_b32 s15, 0
.Lgb12_spin:
	global_load_dword v2, v1, s[0:1] sc1
	s_waitcnt vmcnt(0)
	v_readfirstlane_b32 s13, v2
	s_nop 1
	s_cmp_lt_u32 s13, 48
	s_cbranch_scc1 .Lgb12_again
	s_branch .Lgb12_done

.LBB0_1293:
	s_or_b64 exec, exec, s[6:7]
	s_waitcnt vmcnt(0)
	s_barrier
	s_mov_b64 s[6:7], exec
	v_readlane_b32 s0, v219, 25
	v_readlane_b32 s1, v219, 26
	s_and_b64 s[0:1], s[6:7], s[0:1]
	s_mov_b64 exec, s[0:1]
	s_cbranch_execz .LBB0_1345
	v_readlane_b32 s0, v219, 27
	v_readlane_b32 s1, v219, 28
	v_readlane_b32 s2, v219, 30
	s_waitcnt vmcnt(0) lgkmcnt(0)
	buffer_inv sc1
	s_and_b32 s3, s2, 31
	s_lshl_b32 s3, s3, 7
	s_add_i32 s3, s3, 64
	v_mov_b32_e32 v1, s3
	v_mov_b32_e32 v0, 1
	s_nop 1
	global_atomic_add v1, v0, s[0:1]
	s_mov_b32 s15, 0
.Lgb13_spin:
	global_load_dword v2, v1, s[0:1] sc1
	s_waitcnt vmcnt(0)
	v_readfirstlane_b32 s13, v2
	s_nop 1
	s_cmp_lt_u32 s13, 56
	s_cbranch_scc1 .Lgb13_again
	s_branch .Lgb13_done

.Lgb14_spin:
	global_load_dword v2, v1, s[0:1] sc1
	s_waitcnt vmcnt(0)
	v_readfirstlane_b32 s13, v2
	s_nop 1
	s_cmp_lt_u32 s13, 64
	s_cbranch_scc1 .Lgb14_again
	s_branch .Lgb14_done

.Lgb15_spin:
	global_load_dword v2, v1, s[0:1] sc1
	s_waitcnt vmcnt(0)
	v_readfirstlane_b32 s13, v2
	s_nop 1
	s_cmp_lt_u32 s13, 72
	s_cbranch_scc1 .Lgb15_again
	s_branch .Lgb15_done
